# EpiResB epilogue of out-/down-proj rewritten: residual loads of 7 row groups issued up front with counted vmcnt, batched cross-lane reductions
# baseline (speedup 1.0000x reference)
; __device__ __forceinline__ unsigned cvt_pk_bf16(float lo, float hi) { const f32x2c_t v = {lo, hi}; return __builtin_bit_cast(unsigned, __builtin_convertvector(v, bf16x2c_t)); }
;     __device__ __forceinline__ void operator()(const f32x4 (&acc)[2][2][4][2], const Unit& u, int wr, int wc, int fr, int fq) const {
;         const int row0 = u.pm * BM + wr * 64 + fr, col0 = u.pn * BM + wc * 32 + 8 * fq;
;         u32x4 nb[2];
;         { const bf16_t* rp = X + (size_t)row0 * ldc + col0; nb[0] = *(const u32x4*)(rp); nb[1] = *(const u32x4*)(rp + HALF); }
; #pragma unroll
;         for (int gi = 0; gi < 8; ++gi) { const int ai = gi >> 2, m = gi & 3;
;             const int row = row0 + ai * HALF + m * 16; bf16_t* rowp = X + (size_t)row * ldc + col0;
;             u32x4 b[2]; b[0] = nb[0]; b[1] = nb[1];
;             if (gi < 7) { const bf16_t* rp = X + (size_t)(row0 + ((gi + 1) >> 2) * HALF + ((gi + 1) & 3) * 16) * ldc + col0; nb[0] = *(const u32x4*)(rp); nb[1] = *(const u32x4*)(rp + HALF); }
;             float ss = 0.f;
; #pragma unroll
;             for (int bj = 0; bj < 2; ++bj) {
;                 f32x4 v0 = acc[ai][bj][m][0], v1 = acc[ai][bj][m][1];
;                 v0[0] += __uint_as_float(b[bj].x << 16); v0[1] += __uint_as_float(b[bj].x & 0xffff0000u); v0[2] += __uint_as_float(b[bj].y << 16); v0[3] += __uint_as_float(b[bj].y & 0xffff0000u);
;                 v1[0] += __uint_as_float(b[bj].z << 16); v1[1] += __uint_as_float(b[bj].z & 0xffff0000u); v1[2] += __uint_as_float(b[bj].w << 16); v1[3] += __uint_as_float(b[bj].w & 0xffff0000u);
;                 ss += ((v0[0] * v0[0] + v0[1] * v0[1]) + (v0[2] * v0[2] + v0[3] * v0[3])) + ((v1[0] * v1[0] + v1[1] * v1[1]) + (v1[2] * v1[2] + v1[3] * v1[3]));
;                 u32x4 w; w.x = cvt_pk_bf16(v0[0], v0[1]); w.y = cvt_pk_bf16(v0[2], v0[3]); w.z = cvt_pk_bf16(v1[0], v1[1]); w.w = cvt_pk_bf16(v1[2], v1[3]);
;                 *(u32x4*)(rowp + bj * HALF) = w; }
.LBB0_561:
	v_lshl_add_u32 v150, s78, 8, v156
	v_lshl_or_b32 v148, s73, 8, v158
	v_lshlrev_b32_e32 v151, 13, v150
	v_lshl_add_u32 v151, v148, 1, v151
	global_load_dwordx4 v[130:133], v151, s[56:57]
	global_load_dwordx4 v[134:137], v151, s[56:57] offset:256
	s_add_u32 s0, s56, 0x20000
	s_addc_u32 s1, s57, 0
	global_load_dwordx4 v[162:165], v151, s[0:1]
	global_load_dwordx4 v[166:169], v151, s[0:1] offset:256
	s_add_u32 s0, s56, 0x40000
	s_addc_u32 s1, s57, 0
	global_load_dwordx4 v[170:173], v151, s[0:1]
	global_load_dwordx4 v[174:177], v151, s[0:1] offset:256
	s_add_u32 s0, s56, 0x60000
	s_addc_u32 s1, s57, 0
	global_load_dwordx4 v[178:181], v151, s[0:1]
	global_load_dwordx4 v[182:185], v151, s[0:1] offset:256
	s_add_u32 s0, s56, 0x100000
	s_addc_u32 s1, s57, 0
	global_load_dwordx4 v[186:189], v151, s[0:1]
	global_load_dwordx4 v[190:193], v151, s[0:1] offset:256
	s_add_u32 s0, s56, 0x120000
	s_addc_u32 s1, s57, 0
	global_load_dwordx4 v[194:197], v151, s[0:1]
	global_load_dwordx4 v[198:201], v151, s[0:1] offset:256
	s_add_u32 s0, s56, 0x140000
	s_addc_u32 s1, s57, 0
	global_load_dwordx4 v[202:205], v151, s[0:1]
	global_load_dwordx4 v[206:209], v151, s[0:1] offset:256
	s_lshl_b32 s6, s73, 4
	s_lshl_b32 s7, s51, 2
	s_add_u32 s6, s6, s7
	v_lshl_add_u32 v149, v150, 8, s6
	s_waitcnt vmcnt(12)
	v_lshlrev_b32_e32 v152, 16, v130
	v_and_b32_e32 v153, 0xffff0000, v130
	v_pk_add_f32 v[126:127], v[126:127], v[152:153]
	v_lshlrev_b32_e32 v152, 16, v131
	v_and_b32_e32 v153, 0xffff0000, v131
	v_pk_add_f32 v[128:129], v[128:129], v[152:153]
	v_lshlrev_b32_e32 v152, 16, v132
	v_and_b32_e32 v153, 0xffff0000, v132
	v_pk_add_f32 v[122:123], v[122:123], v[152:153]
	v_lshlrev_b32_e32 v152, 16, v133
	v_and_b32_e32 v153, 0xffff0000, v133
	v_pk_add_f32 v[124:125], v[124:125], v[152:153]
	v_cvt_pk_bf16_f32 v130, v126, v127
	v_cvt_pk_bf16_f32 v131, v128, v129
	v_cvt_pk_bf16_f32 v132, v122, v123
	v_cvt_pk_bf16_f32 v133, v124, v125
	global_store_dwordx4 v151, v[130:133], s[56:57]
	v_pk_mul_f32 v[126:127], v[126:127], v[126:127]
	v_pk_mul_f32 v[128:129], v[128:129], v[128:129]
	v_pk_mul_f32 v[122:123], v[122:123], v[122:123]
	v_pk_mul_f32 v[124:125], v[124:125], v[124:125]
	v_add_f32_e32 v126, v126, v127
	v_add_f32_e32 v128, v128, v129
	v_add_f32_e32 v122, v122, v123
	v_add_f32_e32 v124, v124, v125
	v_add_f32_e32 v126, v126, v128
	v_add_f32_e32 v122, v122, v124
	v_add_f32_e32 v126, v126, v122
	v_lshlrev_b32_e32 v152, 16, v134
	v_and_b32_e32 v153, 0xffff0000, v134
	v_pk_add_f32 v[118:119], v[118:119], v[152:153]
	v_lshlrev_b32_e32 v152, 16, v135
	v_and_b32_e32 v153, 0xffff0000, v135
	v_pk_add_f32 v[120:121], v[120:121], v[152:153]
	v_lshlrev_b32_e32 v152, 16, v136
	v_and_b32_e32 v153, 0xffff0000, v136
	v_pk_add_f32 v[114:115], v[114:115], v[152:153]
	v_lshlrev_b32_e32 v152, 16, v137
	v_and_b32_e32 v153, 0xffff0000, v137
	v_pk_add_f32 v[116:117], v[116:117], v[152:153]
	v_cvt_pk_bf16_f32 v134, v118, v119
	v_cvt_pk_bf16_f32 v135, v120, v121
	v_cvt_pk_bf16_f32 v136, v114, v115
	v_cvt_pk_bf16_f32 v137, v116, v117
	global_store_dwordx4 v151, v[134:137], s[56:57] offset:256
	v_pk_mul_f32 v[118:119], v[118:119], v[118:119]
	v_pk_mul_f32 v[120:121], v[120:121], v[120:121]
	v_pk_mul_f32 v[114:115], v[114:115], v[114:115]
	v_pk_mul_f32 v[116:117], v[116:117], v[116:117]
	v_add_f32_e32 v118, v118, v119
	v_add_f32_e32 v120, v120, v121
	v_add_f32_e32 v114, v114, v115
	v_add_f32_e32 v116, v116, v117
	v_add_f32_e32 v118, v118, v120
	v_add_f32_e32 v114, v114, v116
	v_add_f32_e32 v118, v118, v114
	v_add_f32_e32 v126, v126, v118
	s_add_u32 s0, s56, 0x160000
	s_addc_u32 s1, s57, 0
	global_load_dwordx4 v[118:121], v151, s[0:1]
	global_load_dwordx4 v[122:125], v151, s[0:1] offset:256
	s_waitcnt vmcnt(14)
	s_add_u32 s0, s56, 0x20000
	s_addc_u32 s1, s57, 0
	v_lshlrev_b32_e32 v152, 16, v162
	v_and_b32_e32 v153, 0xffff0000, v162
	v_pk_add_f32 v[110:111], v[110:111], v[152:153]
	v_lshlrev_b32_e32 v152, 16, v163
	v_and_b32_e32 v153, 0xffff0000, v163
	v_pk_add_f32 v[112:113], v[112:113], v[152:153]
	v_lshlrev_b32_e32 v152, 16, v164
	v_and_b32_e32 v153, 0xffff0000, v164
	v_pk_add_f32 v[106:107], v[106:107], v[152:153]
	v_lshlrev_b32_e32 v152, 16, v165
	v_and_b32_e32 v153, 0xffff0000, v165
	v_pk_add_f32 v[108:109], v[108:109], v[152:153]
	v_cvt_pk_bf16_f32 v162, v110, v111
	v_cvt_pk_bf16_f32 v163, v112, v113
	v_cvt_pk_bf16_f32 v164, v106, v107
	v_cvt_pk_bf16_f32 v165, v108, v109
	global_store_dwordx4 v151, v[162:165], s[0:1]
	v_pk_mul_f32 v[110:111], v[110:111], v[110:111]
	v_pk_mul_f32 v[112:113], v[112:113], v[112:113]
	v_pk_mul_f32 v[106:107], v[106:107], v[106:107]
	v_pk_mul_f32 v[108:109], v[108:109], v[108:109]
	v_add_f32_e32 v110, v110, v111
	v_add_f32_e32 v112, v112, v113
	v_add_f32_e32 v106, v106, v107
	v_add_f32_e32 v108, v108, v109
	v_add_f32_e32 v110, v110, v112
	v_add_f32_e32 v106, v106, v108
	v_add_f32_e32 v110, v110, v106
	v_lshlrev_b32_e32 v152, 16, v166
	v_and_b32_e32 v153, 0xffff0000, v166
	v_pk_add_f32 v[102:103], v[102:103], v[152:153]
	v_lshlrev_b32_e32 v152, 16, v167
	v_and_b32_e32 v153, 0xffff0000, v167
	v_pk_add_f32 v[104:105], v[104:105], v[152:153]
	v_lshlrev_b32_e32 v152, 16, v168
	v_and_b32_e32 v153, 0xffff0000, v168
	v_pk_add_f32 v[98:99], v[98:99], v[152:153]
	v_lshlrev_b32_e32 v152, 16, v169
	v_and_b32_e32 v153, 0xffff0000, v169
	v_pk_add_f32 v[100:101], v[100:101], v[152:153]
	v_cvt_pk_bf16_f32 v166, v102, v103
	v_cvt_pk_bf16_f32 v167, v104, v105
	v_cvt_pk_bf16_f32 v168, v98, v99
	v_cvt_pk_bf16_f32 v169, v100, v101
	global_store_dwordx4 v151, v[166:169], s[0:1] offset:256
	v_pk_mul_f32 v[102:103], v[102:103], v[102:103]
	v_pk_mul_f32 v[104:105], v[104:105], v[104:105]
	v_pk_mul_f32 v[98:99], v[98:99], v[98:99]
	v_pk_mul_f32 v[100:101], v[100:101], v[100:101]
	v_add_f32_e32 v102, v102, v103
	v_add_f32_e32 v104, v104, v105
	v_add_f32_e32 v98, v98, v99
	v_add_f32_e32 v100, v100, v101
	v_add_f32_e32 v102, v102, v104
	v_add_f32_e32 v98, v98, v100
	v_add_f32_e32 v102, v102, v98
	v_add_f32_e32 v110, v110, v102
	s_waitcnt vmcnt(14)
; __device__ __forceinline__ unsigned cvt_pk_bf16(float lo, float hi) { const f32x2c_t v = {lo, hi}; return __builtin_bit_cast(unsigned, __builtin_convertvector(v, bf16x2c_t)); }
;     __device__ __forceinline__ void operator()(const f32x4 (&acc)[2][2][4][2], const Unit& u, int wr, int wc, int fr, int fq) const {
;     ...
;             for (int bj = 0; bj < 2; ++bj) {
;                 f32x4 v0 = acc[ai][bj][m][0], v1 = acc[ai][bj][m][1];
;                 v0[0] += __uint_as_float(b[bj].x << 16); v0[1] += __uint_as_float(b[bj].x & 0xffff0000u); v0[2] += __uint_as_float(b[bj].y << 16); v0[3] += __uint_as_float(b[bj].y & 0xffff0000u);
;                 v1[0] += __uint_as_float(b[bj].z << 16); v1[1] += __uint_as_float(b[bj].z & 0xffff0000u); v1[2] += __uint_as_float(b[bj].w << 16); v1[3] += __uint_as_float(b[bj].w & 0xffff0000u);
;                 ss += ((v0[0] * v0[0] + v0[1] * v0[1]) + (v0[2] * v0[2] + v0[3] * v0[3])) + ((v1[0] * v1[0] + v1[1] * v1[1]) + (v1[2] * v1[2] + v1[3] * v1[3]));
;                 u32x4 w; w.x = cvt_pk_bf16(v0[0], v0[1]); w.y = cvt_pk_bf16(v0[2], v0[3]); w.z = cvt_pk_bf16(v1[0], v1[1]); w.w = cvt_pk_bf16(v1[2], v1[3]);
;                 *(u32x4*)(rowp + bj * HALF) = w; }
	s_add_u32 s0, s56, 0x40000
	s_addc_u32 s1, s57, 0
	v_lshlrev_b32_e32 v152, 16, v170
	v_and_b32_e32 v153, 0xffff0000, v170
	v_pk_add_f32 v[94:95], v[94:95], v[152:153]
	v_lshlrev_b32_e32 v152, 16, v171
	v_and_b32_e32 v153, 0xffff0000, v171
	v_pk_add_f32 v[96:97], v[96:97], v[152:153]
	v_lshlrev_b32_e32 v152, 16, v172
	v_and_b32_e32 v153, 0xffff0000, v172
	v_pk_add_f32 v[90:91], v[90:91], v[152:153]
	v_lshlrev_b32_e32 v152, 16, v173
	v_and_b32_e32 v153, 0xffff0000, v173
	v_pk_add_f32 v[92:93], v[92:93], v[152:153]
	v_cvt_pk_bf16_f32 v170, v94, v95
	v_cvt_pk_bf16_f32 v171, v96, v97
	v_cvt_pk_bf16_f32 v172, v90, v91
	v_cvt_pk_bf16_f32 v173, v92, v93
	global_store_dwordx4 v151, v[170:173], s[0:1]
	v_pk_mul_f32 v[94:95], v[94:95], v[94:95]
	v_pk_mul_f32 v[96:97], v[96:97], v[96:97]
	v_pk_mul_f32 v[90:91], v[90:91], v[90:91]
	v_pk_mul_f32 v[92:93], v[92:93], v[92:93]
	v_add_f32_e32 v94, v94, v95
	v_add_f32_e32 v96, v96, v97
	v_add_f32_e32 v90, v90, v91
	v_add_f32_e32 v92, v92, v93
	v_add_f32_e32 v94, v94, v96
	v_add_f32_e32 v90, v90, v92
	v_add_f32_e32 v94, v94, v90
	v_lshlrev_b32_e32 v152, 16, v174
	v_and_b32_e32 v153, 0xffff0000, v174
	v_pk_add_f32 v[86:87], v[86:87], v[152:153]
	v_lshlrev_b32_e32 v152, 16, v175
	v_and_b32_e32 v153, 0xffff0000, v175
	v_pk_add_f32 v[88:89], v[88:89], v[152:153]
	v_lshlrev_b32_e32 v152, 16, v176
	v_and_b32_e32 v153, 0xffff0000, v176
	v_pk_add_f32 v[82:83], v[82:83], v[152:153]
	v_lshlrev_b32_e32 v152, 16, v177
	v_and_b32_e32 v153, 0xffff0000, v177
	v_pk_add_f32 v[84:85], v[84:85], v[152:153]
	v_cvt_pk_bf16_f32 v174, v86, v87
	v_cvt_pk_bf16_f32 v175, v88, v89
	v_cvt_pk_bf16_f32 v176, v82, v83
	v_cvt_pk_bf16_f32 v177, v84, v85
	global_store_dwordx4 v151, v[174:177], s[0:1] offset:256
	v_pk_mul_f32 v[86:87], v[86:87], v[86:87]
	v_pk_mul_f32 v[88:89], v[88:89], v[88:89]
	v_pk_mul_f32 v[82:83], v[82:83], v[82:83]
	v_pk_mul_f32 v[84:85], v[84:85], v[84:85]
	v_add_f32_e32 v86, v86, v87
	v_add_f32_e32 v88, v88, v89
	v_add_f32_e32 v82, v82, v83
	v_add_f32_e32 v84, v84, v85
	v_add_f32_e32 v86, v86, v88
	v_add_f32_e32 v82, v82, v84
	v_add_f32_e32 v86, v86, v82
	v_add_f32_e32 v94, v94, v86
	s_waitcnt vmcnt(14)
	s_add_u32 s0, s56, 0x60000
	s_addc_u32 s1, s57, 0
	v_lshlrev_b32_e32 v152, 16, v178
	v_and_b32_e32 v153, 0xffff0000, v178
	v_pk_add_f32 v[78:79], v[78:79], v[152:153]
	v_lshlrev_b32_e32 v152, 16, v179
	v_and_b32_e32 v153, 0xffff0000, v179
	v_pk_add_f32 v[80:81], v[80:81], v[152:153]
	v_lshlrev_b32_e32 v152, 16, v180
	v_and_b32_e32 v153, 0xffff0000, v180
	v_pk_add_f32 v[74:75], v[74:75], v[152:153]
	v_lshlrev_b32_e32 v152, 16, v181
	v_and_b32_e32 v153, 0xffff0000, v181
	v_pk_add_f32 v[76:77], v[76:77], v[152:153]
	v_cvt_pk_bf16_f32 v178, v78, v79
	v_cvt_pk_bf16_f32 v179, v80, v81
	v_cvt_pk_bf16_f32 v180, v74, v75
	v_cvt_pk_bf16_f32 v181, v76, v77
	global_store_dwordx4 v151, v[178:181], s[0:1]
	v_pk_mul_f32 v[78:79], v[78:79], v[78:79]
	v_pk_mul_f32 v[80:81], v[80:81], v[80:81]
	v_pk_mul_f32 v[74:75], v[74:75], v[74:75]
	v_pk_mul_f32 v[76:77], v[76:77], v[76:77]
	v_add_f32_e32 v78, v78, v79
	v_add_f32_e32 v80, v80, v81
	v_add_f32_e32 v74, v74, v75
	v_add_f32_e32 v76, v76, v77
	v_add_f32_e32 v78, v78, v80
	v_add_f32_e32 v74, v74, v76
	v_add_f32_e32 v78, v78, v74
	v_lshlrev_b32_e32 v152, 16, v182
	v_and_b32_e32 v153, 0xffff0000, v182
	v_pk_add_f32 v[70:71], v[70:71], v[152:153]
	v_lshlrev_b32_e32 v152, 16, v183
	v_and_b32_e32 v153, 0xffff0000, v183
	v_pk_add_f32 v[72:73], v[72:73], v[152:153]
	v_lshlrev_b32_e32 v152, 16, v184
	v_and_b32_e32 v153, 0xffff0000, v184
	v_pk_add_f32 v[66:67], v[66:67], v[152:153]
	v_lshlrev_b32_e32 v152, 16, v185
	v_and_b32_e32 v153, 0xffff0000, v185
	v_pk_add_f32 v[68:69], v[68:69], v[152:153]
	v_cvt_pk_bf16_f32 v182, v70, v71
	v_cvt_pk_bf16_f32 v183, v72, v73
	v_cvt_pk_bf16_f32 v184, v66, v67
	v_cvt_pk_bf16_f32 v185, v68, v69
	global_store_dwordx4 v151, v[182:185], s[0:1] offset:256
	v_pk_mul_f32 v[70:71], v[70:71], v[70:71]
	v_pk_mul_f32 v[72:73], v[72:73], v[72:73]
	v_pk_mul_f32 v[66:67], v[66:67], v[66:67]
	v_pk_mul_f32 v[68:69], v[68:69], v[68:69]
	v_add_f32_e32 v70, v70, v71
	v_add_f32_e32 v72, v72, v73
	v_add_f32_e32 v66, v66, v67
	v_add_f32_e32 v68, v68, v69
	v_add_f32_e32 v70, v70, v72
	v_add_f32_e32 v66, v66, v68
	v_add_f32_e32 v70, v70, v66
	v_add_f32_e32 v78, v78, v70
	s_waitcnt vmcnt(14)
	s_add_u32 s0, s56, 0x100000
	s_addc_u32 s1, s57, 0
	v_lshlrev_b32_e32 v152, 16, v186
	v_and_b32_e32 v153, 0xffff0000, v186
	v_pk_add_f32 v[62:63], v[62:63], v[152:153]
	v_lshlrev_b32_e32 v152, 16, v187
	v_and_b32_e32 v153, 0xffff0000, v187
	v_pk_add_f32 v[64:65], v[64:65], v[152:153]
	v_lshlrev_b32_e32 v152, 16, v188
	v_and_b32_e32 v153, 0xffff0000, v188
	v_pk_add_f32 v[58:59], v[58:59], v[152:153]
	v_lshlrev_b32_e32 v152, 16, v189
	v_and_b32_e32 v153, 0xffff0000, v189
	v_pk_add_f32 v[60:61], v[60:61], v[152:153]
	v_cvt_pk_bf16_f32 v186, v62, v63
	v_cvt_pk_bf16_f32 v187, v64, v65
	v_cvt_pk_bf16_f32 v188, v58, v59
	v_cvt_pk_bf16_f32 v189, v60, v61
	global_store_dwordx4 v151, v[186:189], s[0:1]
	v_pk_mul_f32 v[62:63], v[62:63], v[62:63]
	v_pk_mul_f32 v[64:65], v[64:65], v[64:65]
	v_pk_mul_f32 v[58:59], v[58:59], v[58:59]
	v_pk_mul_f32 v[60:61], v[60:61], v[60:61]
	v_add_f32_e32 v62, v62, v63
	v_add_f32_e32 v64, v64, v65
	v_add_f32_e32 v58, v58, v59
	v_add_f32_e32 v60, v60, v61
	v_add_f32_e32 v62, v62, v64
	v_add_f32_e32 v58, v58, v60
	v_add_f32_e32 v62, v62, v58
	v_lshlrev_b32_e32 v152, 16, v190
	v_and_b32_e32 v153, 0xffff0000, v190
	v_pk_add_f32 v[54:55], v[54:55], v[152:153]
	v_lshlrev_b32_e32 v152, 16, v191
	v_and_b32_e32 v153, 0xffff0000, v191
	v_pk_add_f32 v[56:57], v[56:57], v[152:153]
	v_lshlrev_b32_e32 v152, 16, v192
	v_and_b32_e32 v153, 0xffff0000, v192
	v_pk_add_f32 v[50:51], v[50:51], v[152:153]
	v_lshlrev_b32_e32 v152, 16, v193
	v_and_b32_e32 v153, 0xffff0000, v193
	v_pk_add_f32 v[52:53], v[52:53], v[152:153]
	v_cvt_pk_bf16_f32 v190, v54, v55
	v_cvt_pk_bf16_f32 v191, v56, v57
	v_cvt_pk_bf16_f32 v192, v50, v51
	v_cvt_pk_bf16_f32 v193, v52, v53
	global_store_dwordx4 v151, v[190:193], s[0:1] offset:256
	v_pk_mul_f32 v[54:55], v[54:55], v[54:55]
	v_pk_mul_f32 v[56:57], v[56:57], v[56:57]
	v_pk_mul_f32 v[50:51], v[50:51], v[50:51]
	v_pk_mul_f32 v[52:53], v[52:53], v[52:53]
	v_add_f32_e32 v54, v54, v55
	v_add_f32_e32 v56, v56, v57
	v_add_f32_e32 v50, v50, v51
	v_add_f32_e32 v52, v52, v53
	v_add_f32_e32 v54, v54, v56
	v_add_f32_e32 v50, v50, v52
	v_add_f32_e32 v54, v54, v50
	v_add_f32_e32 v62, v62, v54
	s_waitcnt vmcnt(14)
; __device__ __forceinline__ unsigned cvt_pk_bf16(float lo, float hi) { const f32x2c_t v = {lo, hi}; return __builtin_bit_cast(unsigned, __builtin_convertvector(v, bf16x2c_t)); }
;     __device__ __forceinline__ void operator()(const f32x4 (&acc)[2][2][4][2], const Unit& u, int wr, int wc, int fr, int fq) const {
;     ...
;             for (int bj = 0; bj < 2; ++bj) {
;                 f32x4 v0 = acc[ai][bj][m][0], v1 = acc[ai][bj][m][1];
;                 v0[0] += __uint_as_float(b[bj].x << 16); v0[1] += __uint_as_float(b[bj].x & 0xffff0000u); v0[2] += __uint_as_float(b[bj].y << 16); v0[3] += __uint_as_float(b[bj].y & 0xffff0000u);
;                 v1[0] += __uint_as_float(b[bj].z << 16); v1[1] += __uint_as_float(b[bj].z & 0xffff0000u); v1[2] += __uint_as_float(b[bj].w << 16); v1[3] += __uint_as_float(b[bj].w & 0xffff0000u);
;                 ss += ((v0[0] * v0[0] + v0[1] * v0[1]) + (v0[2] * v0[2] + v0[3] * v0[3])) + ((v1[0] * v1[0] + v1[1] * v1[1]) + (v1[2] * v1[2] + v1[3] * v1[3]));
;                 u32x4 w; w.x = cvt_pk_bf16(v0[0], v0[1]); w.y = cvt_pk_bf16(v0[2], v0[3]); w.z = cvt_pk_bf16(v1[0], v1[1]); w.w = cvt_pk_bf16(v1[2], v1[3]);
;                 *(u32x4*)(rowp + bj * HALF) = w; }
	s_add_u32 s0, s56, 0x120000
	s_addc_u32 s1, s57, 0
	v_lshlrev_b32_e32 v152, 16, v194
	v_and_b32_e32 v153, 0xffff0000, v194
	v_pk_add_f32 v[46:47], v[46:47], v[152:153]
	v_lshlrev_b32_e32 v152, 16, v195
	v_and_b32_e32 v153, 0xffff0000, v195
	v_pk_add_f32 v[48:49], v[48:49], v[152:153]
	v_lshlrev_b32_e32 v152, 16, v196
	v_and_b32_e32 v153, 0xffff0000, v196
	v_pk_add_f32 v[42:43], v[42:43], v[152:153]
	v_lshlrev_b32_e32 v152, 16, v197
	v_and_b32_e32 v153, 0xffff0000, v197
	v_pk_add_f32 v[44:45], v[44:45], v[152:153]
	v_cvt_pk_bf16_f32 v194, v46, v47
	v_cvt_pk_bf16_f32 v195, v48, v49
	v_cvt_pk_bf16_f32 v196, v42, v43
	v_cvt_pk_bf16_f32 v197, v44, v45
	global_store_dwordx4 v151, v[194:197], s[0:1]
	v_pk_mul_f32 v[46:47], v[46:47], v[46:47]
	v_pk_mul_f32 v[48:49], v[48:49], v[48:49]
	v_pk_mul_f32 v[42:43], v[42:43], v[42:43]
	v_pk_mul_f32 v[44:45], v[44:45], v[44:45]
	v_add_f32_e32 v46, v46, v47
	v_add_f32_e32 v48, v48, v49
	v_add_f32_e32 v42, v42, v43
	v_add_f32_e32 v44, v44, v45
	v_add_f32_e32 v46, v46, v48
	v_add_f32_e32 v42, v42, v44
	v_add_f32_e32 v46, v46, v42
	v_lshlrev_b32_e32 v152, 16, v198
	v_and_b32_e32 v153, 0xffff0000, v198
	v_pk_add_f32 v[38:39], v[38:39], v[152:153]
	v_lshlrev_b32_e32 v152, 16, v199
	v_and_b32_e32 v153, 0xffff0000, v199
	v_pk_add_f32 v[40:41], v[40:41], v[152:153]
	v_lshlrev_b32_e32 v152, 16, v200
	v_and_b32_e32 v153, 0xffff0000, v200
	v_pk_add_f32 v[34:35], v[34:35], v[152:153]
	v_lshlrev_b32_e32 v152, 16, v201
	v_and_b32_e32 v153, 0xffff0000, v201
	v_pk_add_f32 v[36:37], v[36:37], v[152:153]
	v_cvt_pk_bf16_f32 v198, v38, v39
	v_cvt_pk_bf16_f32 v199, v40, v41
	v_cvt_pk_bf16_f32 v200, v34, v35
	v_cvt_pk_bf16_f32 v201, v36, v37
	global_store_dwordx4 v151, v[198:201], s[0:1] offset:256
	v_pk_mul_f32 v[38:39], v[38:39], v[38:39]
	v_pk_mul_f32 v[40:41], v[40:41], v[40:41]
	v_pk_mul_f32 v[34:35], v[34:35], v[34:35]
	v_pk_mul_f32 v[36:37], v[36:37], v[36:37]
	v_add_f32_e32 v38, v38, v39
	v_add_f32_e32 v40, v40, v41
	v_add_f32_e32 v34, v34, v35
	v_add_f32_e32 v36, v36, v37
	v_add_f32_e32 v38, v38, v40
	v_add_f32_e32 v34, v34, v36
	v_add_f32_e32 v38, v38, v34
	v_add_f32_e32 v46, v46, v38
	s_waitcnt vmcnt(14)
	s_add_u32 s0, s56, 0x140000
	s_addc_u32 s1, s57, 0
	v_lshlrev_b32_e32 v152, 16, v202
	v_and_b32_e32 v153, 0xffff0000, v202
	v_pk_add_f32 v[30:31], v[30:31], v[152:153]
	v_lshlrev_b32_e32 v152, 16, v203
	v_and_b32_e32 v153, 0xffff0000, v203
	v_pk_add_f32 v[32:33], v[32:33], v[152:153]
	v_lshlrev_b32_e32 v152, 16, v204
	v_and_b32_e32 v153, 0xffff0000, v204
	v_pk_add_f32 v[26:27], v[26:27], v[152:153]
	v_lshlrev_b32_e32 v152, 16, v205
	v_and_b32_e32 v153, 0xffff0000, v205
	v_pk_add_f32 v[28:29], v[28:29], v[152:153]
	v_cvt_pk_bf16_f32 v202, v30, v31
	v_cvt_pk_bf16_f32 v203, v32, v33
	v_cvt_pk_bf16_f32 v204, v26, v27
	v_cvt_pk_bf16_f32 v205, v28, v29
	global_store_dwordx4 v151, v[202:205], s[0:1]
	v_pk_mul_f32 v[30:31], v[30:31], v[30:31]
	v_pk_mul_f32 v[32:33], v[32:33], v[32:33]
	v_pk_mul_f32 v[26:27], v[26:27], v[26:27]
	v_pk_mul_f32 v[28:29], v[28:29], v[28:29]
	v_add_f32_e32 v30, v30, v31
	v_add_f32_e32 v32, v32, v33
	v_add_f32_e32 v26, v26, v27
	v_add_f32_e32 v28, v28, v29
	v_add_f32_e32 v30, v30, v32
	v_add_f32_e32 v26, v26, v28
	v_add_f32_e32 v30, v30, v26
	v_lshlrev_b32_e32 v152, 16, v206
	v_and_b32_e32 v153, 0xffff0000, v206
	v_pk_add_f32 v[22:23], v[22:23], v[152:153]
	v_lshlrev_b32_e32 v152, 16, v207
	v_and_b32_e32 v153, 0xffff0000, v207
	v_pk_add_f32 v[24:25], v[24:25], v[152:153]
	v_lshlrev_b32_e32 v152, 16, v208
	v_and_b32_e32 v153, 0xffff0000, v208
	v_pk_add_f32 v[18:19], v[18:19], v[152:153]
	v_lshlrev_b32_e32 v152, 16, v209
	v_and_b32_e32 v153, 0xffff0000, v209
	v_pk_add_f32 v[20:21], v[20:21], v[152:153]
	v_cvt_pk_bf16_f32 v206, v22, v23
	v_cvt_pk_bf16_f32 v207, v24, v25
	v_cvt_pk_bf16_f32 v208, v18, v19
	v_cvt_pk_bf16_f32 v209, v20, v21
	global_store_dwordx4 v151, v[206:209], s[0:1] offset:256
	v_pk_mul_f32 v[22:23], v[22:23], v[22:23]
	v_pk_mul_f32 v[24:25], v[24:25], v[24:25]
	v_pk_mul_f32 v[18:19], v[18:19], v[18:19]
	v_pk_mul_f32 v[20:21], v[20:21], v[20:21]
	v_add_f32_e32 v22, v22, v23
	v_add_f32_e32 v24, v24, v25
	v_add_f32_e32 v18, v18, v19
	v_add_f32_e32 v20, v20, v21
	v_add_f32_e32 v22, v22, v24
	v_add_f32_e32 v18, v18, v20
	v_add_f32_e32 v22, v22, v18
	v_add_f32_e32 v30, v30, v22
	s_waitcnt vmcnt(12)
; __device__ __forceinline__ unsigned cvt_pk_bf16(float lo, float hi) { const f32x2c_t v = {lo, hi}; return __builtin_bit_cast(unsigned, __builtin_convertvector(v, bf16x2c_t)); }
;     __device__ __forceinline__ void operator()(const f32x4 (&acc)[2][2][4][2], const Unit& u, int wr, int wc, int fr, int fq) const {
;     ...
;             for (int bj = 0; bj < 2; ++bj) {
;                 f32x4 v0 = acc[ai][bj][m][0], v1 = acc[ai][bj][m][1];
;                 v0[0] += __uint_as_float(b[bj].x << 16); v0[1] += __uint_as_float(b[bj].x & 0xffff0000u); v0[2] += __uint_as_float(b[bj].y << 16); v0[3] += __uint_as_float(b[bj].y & 0xffff0000u);
;                 v1[0] += __uint_as_float(b[bj].z << 16); v1[1] += __uint_as_float(b[bj].z & 0xffff0000u); v1[2] += __uint_as_float(b[bj].w << 16); v1[3] += __uint_as_float(b[bj].w & 0xffff0000u);
;                 ss += ((v0[0] * v0[0] + v0[1] * v0[1]) + (v0[2] * v0[2] + v0[3] * v0[3])) + ((v1[0] * v1[0] + v1[1] * v1[1]) + (v1[2] * v1[2] + v1[3] * v1[3]));
;                 u32x4 w; w.x = cvt_pk_bf16(v0[0], v0[1]); w.y = cvt_pk_bf16(v0[2], v0[3]); w.z = cvt_pk_bf16(v1[0], v1[1]); w.w = cvt_pk_bf16(v1[2], v1[3]);
;                 *(u32x4*)(rowp + bj * HALF) = w; }
;             ss += __shfl_xor(ss, 16); ss += __shfl_xor(ss, 32);
;             if (fq == 0) part[(size_t)row * 64 + u.pn * 4 + wc] = ss; }
	s_add_u32 s0, s56, 0x160000
	s_addc_u32 s1, s57, 0
	v_lshlrev_b32_e32 v152, 16, v118
	v_and_b32_e32 v153, 0xffff0000, v118
	v_pk_add_f32 v[12:13], v[12:13], v[152:153]
	v_lshlrev_b32_e32 v152, 16, v119
	v_and_b32_e32 v153, 0xffff0000, v119
	v_pk_add_f32 v[14:15], v[14:15], v[152:153]
	v_lshlrev_b32_e32 v152, 16, v120
	v_and_b32_e32 v153, 0xffff0000, v120
	v_pk_add_f32 v[8:9], v[8:9], v[152:153]
	v_lshlrev_b32_e32 v152, 16, v121
	v_and_b32_e32 v153, 0xffff0000, v121
	v_pk_add_f32 v[10:11], v[10:11], v[152:153]
	v_cvt_pk_bf16_f32 v118, v12, v13
	v_cvt_pk_bf16_f32 v119, v14, v15
	v_cvt_pk_bf16_f32 v120, v8, v9
	v_cvt_pk_bf16_f32 v121, v10, v11
	global_store_dwordx4 v151, v[118:121], s[0:1]
	v_pk_mul_f32 v[12:13], v[12:13], v[12:13]
	v_pk_mul_f32 v[14:15], v[14:15], v[14:15]
	v_pk_mul_f32 v[8:9], v[8:9], v[8:9]
	v_pk_mul_f32 v[10:11], v[10:11], v[10:11]
	v_add_f32_e32 v12, v12, v13
	v_add_f32_e32 v14, v14, v15
	v_add_f32_e32 v8, v8, v9
	v_add_f32_e32 v10, v10, v11
	v_add_f32_e32 v12, v12, v14
	v_add_f32_e32 v8, v8, v10
	v_add_f32_e32 v12, v12, v8
	v_lshlrev_b32_e32 v152, 16, v122
	v_and_b32_e32 v153, 0xffff0000, v122
	v_pk_add_f32 v[4:5], v[4:5], v[152:153]
	v_lshlrev_b32_e32 v152, 16, v123
	v_and_b32_e32 v153, 0xffff0000, v123
	v_pk_add_f32 v[6:7], v[6:7], v[152:153]
	v_lshlrev_b32_e32 v152, 16, v124
	v_and_b32_e32 v153, 0xffff0000, v124
	v_pk_add_f32 v[0:1], v[0:1], v[152:153]
	v_lshlrev_b32_e32 v152, 16, v125
	v_and_b32_e32 v153, 0xffff0000, v125
	v_pk_add_f32 v[2:3], v[2:3], v[152:153]
	v_cvt_pk_bf16_f32 v122, v4, v5
	v_cvt_pk_bf16_f32 v123, v6, v7
	v_cvt_pk_bf16_f32 v124, v0, v1
	v_cvt_pk_bf16_f32 v125, v2, v3
	global_store_dwordx4 v151, v[122:125], s[0:1] offset:256
	v_pk_mul_f32 v[4:5], v[4:5], v[4:5]
	v_pk_mul_f32 v[6:7], v[6:7], v[6:7]
	v_pk_mul_f32 v[0:1], v[0:1], v[0:1]
	v_pk_mul_f32 v[2:3], v[2:3], v[2:3]
	v_add_f32_e32 v4, v4, v5
	v_add_f32_e32 v6, v6, v7
	v_add_f32_e32 v0, v0, v1
	v_add_f32_e32 v2, v2, v3
	v_add_f32_e32 v4, v4, v6
	v_add_f32_e32 v0, v0, v2
	v_add_f32_e32 v4, v4, v0
	v_add_f32_e32 v12, v12, v4
	ds_bpermute_b32 v127, v159, v126
	ds_bpermute_b32 v111, v159, v110
	ds_bpermute_b32 v95, v159, v94
	ds_bpermute_b32 v79, v159, v78
	ds_bpermute_b32 v63, v159, v62
	ds_bpermute_b32 v47, v159, v46
	ds_bpermute_b32 v31, v159, v30
	ds_bpermute_b32 v13, v159, v12
	s_waitcnt lgkmcnt(7)
	v_add_f32_e32 v126, v126, v127
	ds_bpermute_b32 v127, v160, v126
	s_waitcnt lgkmcnt(7)
	v_add_f32_e32 v110, v110, v111
	ds_bpermute_b32 v111, v160, v110
	s_waitcnt lgkmcnt(7)
	v_add_f32_e32 v94, v94, v95
	ds_bpermute_b32 v95, v160, v94
	s_waitcnt lgkmcnt(7)
	v_add_f32_e32 v78, v78, v79
	ds_bpermute_b32 v79, v160, v78
	s_waitcnt lgkmcnt(7)
	v_add_f32_e32 v62, v62, v63
	ds_bpermute_b32 v63, v160, v62
	s_waitcnt lgkmcnt(7)
	v_add_f32_e32 v46, v46, v47
	ds_bpermute_b32 v47, v160, v46
	s_waitcnt lgkmcnt(7)
	v_add_f32_e32 v30, v30, v31
	ds_bpermute_b32 v31, v160, v30
	s_waitcnt lgkmcnt(7)
	v_add_f32_e32 v12, v12, v13
	ds_bpermute_b32 v13, v160, v12
	s_and_saveexec_b64 s[6:7], s[10:11]
	s_cbranch_execz .Lepires_skip_g2
	s_waitcnt lgkmcnt(7)
	v_add_f32_e32 v126, v126, v127
	global_store_dword v149, v126, s[28:29]
	s_waitcnt lgkmcnt(6)
	v_add_f32_e32 v110, v110, v111
	s_add_u32 s0, s28, 0x1000
	s_addc_u32 s1, s29, 0
	global_store_dword v149, v110, s[0:1]
	s_waitcnt lgkmcnt(5)
	v_add_f32_e32 v94, v94, v95
	s_add_u32 s0, s28, 0x2000
	s_addc_u32 s1, s29, 0
	global_store_dword v149, v94, s[0:1]
	s_waitcnt lgkmcnt(4)
	v_add_f32_e32 v78, v78, v79
	s_add_u32 s0, s28, 0x3000
	s_addc_u32 s1, s29, 0
	global_store_dword v149, v78, s[0:1]
	s_waitcnt lgkmcnt(3)
	v_add_f32_e32 v62, v62, v63
	s_add_u32 s0, s28, 0x8000
	s_addc_u32 s1, s29, 0
	global_store_dword v149, v62, s[0:1]
	s_waitcnt lgkmcnt(2)
	v_add_f32_e32 v46, v46, v47
	s_add_u32 s0, s28, 0x9000
	s_addc_u32 s1, s29, 0
	global_store_dword v149, v46, s[0:1]
	s_waitcnt lgkmcnt(1)
	v_add_f32_e32 v30, v30, v31
	s_add_u32 s0, s28, 0xa000
	s_addc_u32 s1, s29, 0
	global_store_dword v149, v30, s[0:1]
	s_waitcnt lgkmcnt(0)
	v_add_f32_e32 v12, v12, v13
	s_add_u32 s0, s28, 0xb000
	s_addc_u32 s1, s29, 0
	global_store_dword v149, v12, s[0:1]
.Lepires_skip_g2:
	s_or_b64 exec, exec, s[6:7]
	s_waitcnt lgkmcnt(0)
	s_andn2_b64 vcc, exec, s[26:27]
	s_mov_b64 s[0:1], -1
	s_cbranch_vccnz .LBB0_554
	s_andn2_b64 vcc, exec, s[14:15]
	s_cbranch_vccnz .LBB0_553
	s_barrier
	s_branch .LBB0_553

; __device__ __forceinline__ unsigned cvt_pk_bf16(float lo, float hi) { const f32x2c_t v = {lo, hi}; return __builtin_bit_cast(unsigned, __builtin_convertvector(v, bf16x2c_t)); }
;     __device__ __forceinline__ void operator()(const f32x4 (&acc)[2][2][4][2], const Unit& u, int wr, int wc, int fr, int fq) const {
;         const int row0 = u.pm * BM + wr * 64 + fr, col0 = u.pn * BM + wc * 32 + 8 * fq;
;         u32x4 nb[2];
;         { const bf16_t* rp = X + (size_t)row0 * ldc + col0; nb[0] = *(const u32x4*)(rp); nb[1] = *(const u32x4*)(rp + HALF); }
; #pragma unroll
;         for (int gi = 0; gi < 8; ++gi) { const int ai = gi >> 2, m = gi & 3;
;             const int row = row0 + ai * HALF + m * 16; bf16_t* rowp = X + (size_t)row * ldc + col0;
;             u32x4 b[2]; b[0] = nb[0]; b[1] = nb[1];
;             if (gi < 7) { const bf16_t* rp = X + (size_t)(row0 + ((gi + 1) >> 2) * HALF + ((gi + 1) & 3) * 16) * ldc + col0; nb[0] = *(const u32x4*)(rp); nb[1] = *(const u32x4*)(rp + HALF); }
;             float ss = 0.f;
; #pragma unroll
;             for (int bj = 0; bj < 2; ++bj) {
;                 f32x4 v0 = acc[ai][bj][m][0], v1 = acc[ai][bj][m][1];
;                 v0[0] += __uint_as_float(b[bj].x << 16); v0[1] += __uint_as_float(b[bj].x & 0xffff0000u); v0[2] += __uint_as_float(b[bj].y << 16); v0[3] += __uint_as_float(b[bj].y & 0xffff0000u);
;                 v1[0] += __uint_as_float(b[bj].z << 16); v1[1] += __uint_as_float(b[bj].z & 0xffff0000u); v1[2] += __uint_as_float(b[bj].w << 16); v1[3] += __uint_as_float(b[bj].w & 0xffff0000u);
;                 ss += ((v0[0] * v0[0] + v0[1] * v0[1]) + (v0[2] * v0[2] + v0[3] * v0[3])) + ((v1[0] * v1[0] + v1[1] * v1[1]) + (v1[2] * v1[2] + v1[3] * v1[3]));
;                 u32x4 w; w.x = cvt_pk_bf16(v0[0], v0[1]); w.y = cvt_pk_bf16(v0[2], v0[3]); w.z = cvt_pk_bf16(v1[0], v1[1]); w.w = cvt_pk_bf16(v1[2], v1[3]);
;                 *(u32x4*)(rowp + bj * HALF) = w; }
.LBB0_851:
	v_lshl_add_u32 v150, s72, 8, v156
	v_lshl_or_b32 v148, s69, 8, v158
	v_lshlrev_b32_e32 v151, 13, v150
	v_lshl_add_u32 v151, v148, 1, v151
	global_load_dwordx4 v[130:133], v151, s[56:57]
	global_load_dwordx4 v[134:137], v151, s[56:57] offset:256
	s_add_u32 s0, s56, 0x20000
	s_addc_u32 s1, s57, 0
	global_load_dwordx4 v[162:165], v151, s[0:1]
	global_load_dwordx4 v[166:169], v151, s[0:1] offset:256
	s_add_u32 s0, s56, 0x40000
	s_addc_u32 s1, s57, 0
	global_load_dwordx4 v[170:173], v151, s[0:1]
	global_load_dwordx4 v[174:177], v151, s[0:1] offset:256
	s_add_u32 s0, s56, 0x60000
	s_addc_u32 s1, s57, 0
	global_load_dwordx4 v[178:181], v151, s[0:1]
	global_load_dwordx4 v[182:185], v151, s[0:1] offset:256
	s_add_u32 s0, s56, 0x100000
	s_addc_u32 s1, s57, 0
	global_load_dwordx4 v[186:189], v151, s[0:1]
	global_load_dwordx4 v[190:193], v151, s[0:1] offset:256
	s_add_u32 s0, s56, 0x120000
	s_addc_u32 s1, s57, 0
	global_load_dwordx4 v[194:197], v151, s[0:1]
	global_load_dwordx4 v[198:201], v151, s[0:1] offset:256
	s_add_u32 s0, s56, 0x140000
	s_addc_u32 s1, s57, 0
	global_load_dwordx4 v[202:205], v151, s[0:1]
	global_load_dwordx4 v[206:209], v151, s[0:1] offset:256
	s_lshl_b32 s16, s69, 4
	s_lshl_b32 s17, s43, 2
	s_add_u32 s16, s16, s17
	v_lshl_add_u32 v149, v150, 8, s16
	s_waitcnt vmcnt(12)
	v_lshlrev_b32_e32 v152, 16, v130
	v_and_b32_e32 v153, 0xffff0000, v130
	v_pk_add_f32 v[126:127], v[126:127], v[152:153]
	v_lshlrev_b32_e32 v152, 16, v131
	v_and_b32_e32 v153, 0xffff0000, v131
	v_pk_add_f32 v[128:129], v[128:129], v[152:153]
	v_lshlrev_b32_e32 v152, 16, v132
	v_and_b32_e32 v153, 0xffff0000, v132
	v_pk_add_f32 v[122:123], v[122:123], v[152:153]
	v_lshlrev_b32_e32 v152, 16, v133
	v_and_b32_e32 v153, 0xffff0000, v133
	v_pk_add_f32 v[124:125], v[124:125], v[152:153]
	v_cvt_pk_bf16_f32 v130, v126, v127
	v_cvt_pk_bf16_f32 v131, v128, v129
	v_cvt_pk_bf16_f32 v132, v122, v123
	v_cvt_pk_bf16_f32 v133, v124, v125
	global_store_dwordx4 v151, v[130:133], s[56:57]
	v_pk_mul_f32 v[126:127], v[126:127], v[126:127]
	v_pk_mul_f32 v[128:129], v[128:129], v[128:129]
	v_pk_mul_f32 v[122:123], v[122:123], v[122:123]
	v_pk_mul_f32 v[124:125], v[124:125], v[124:125]
	v_add_f32_e32 v126, v126, v127
	v_add_f32_e32 v128, v128, v129
	v_add_f32_e32 v122, v122, v123
	v_add_f32_e32 v124, v124, v125
	v_add_f32_e32 v126, v126, v128
	v_add_f32_e32 v122, v122, v124
	v_add_f32_e32 v126, v126, v122
	v_lshlrev_b32_e32 v152, 16, v134
	v_and_b32_e32 v153, 0xffff0000, v134
	v_pk_add_f32 v[118:119], v[118:119], v[152:153]
	v_lshlrev_b32_e32 v152, 16, v135
	v_and_b32_e32 v153, 0xffff0000, v135
	v_pk_add_f32 v[120:121], v[120:121], v[152:153]
	v_lshlrev_b32_e32 v152, 16, v136
	v_and_b32_e32 v153, 0xffff0000, v136
	v_pk_add_f32 v[114:115], v[114:115], v[152:153]
	v_lshlrev_b32_e32 v152, 16, v137
	v_and_b32_e32 v153, 0xffff0000, v137
	v_pk_add_f32 v[116:117], v[116:117], v[152:153]
	v_cvt_pk_bf16_f32 v134, v118, v119
	v_cvt_pk_bf16_f32 v135, v120, v121
	v_cvt_pk_bf16_f32 v136, v114, v115
	v_cvt_pk_bf16_f32 v137, v116, v117
	global_store_dwordx4 v151, v[134:137], s[56:57] offset:256
	v_pk_mul_f32 v[118:119], v[118:119], v[118:119]
	v_pk_mul_f32 v[120:121], v[120:121], v[120:121]
	v_pk_mul_f32 v[114:115], v[114:115], v[114:115]
	v_pk_mul_f32 v[116:117], v[116:117], v[116:117]
	v_add_f32_e32 v118, v118, v119
	v_add_f32_e32 v120, v120, v121
	v_add_f32_e32 v114, v114, v115
	v_add_f32_e32 v116, v116, v117
	v_add_f32_e32 v118, v118, v120
	v_add_f32_e32 v114, v114, v116
	v_add_f32_e32 v118, v118, v114
	v_add_f32_e32 v126, v126, v118
	s_add_u32 s0, s56, 0x160000
	s_addc_u32 s1, s57, 0
	global_load_dwordx4 v[118:121], v151, s[0:1]
	global_load_dwordx4 v[122:125], v151, s[0:1] offset:256
	s_waitcnt vmcnt(14)
	s_add_u32 s0, s56, 0x20000
	s_addc_u32 s1, s57, 0
	v_lshlrev_b32_e32 v152, 16, v162
	v_and_b32_e32 v153, 0xffff0000, v162
	v_pk_add_f32 v[110:111], v[110:111], v[152:153]
	v_lshlrev_b32_e32 v152, 16, v163
	v_and_b32_e32 v153, 0xffff0000, v163
	v_pk_add_f32 v[112:113], v[112:113], v[152:153]
	v_lshlrev_b32_e32 v152, 16, v164
	v_and_b32_e32 v153, 0xffff0000, v164
	v_pk_add_f32 v[106:107], v[106:107], v[152:153]
	v_lshlrev_b32_e32 v152, 16, v165
	v_and_b32_e32 v153, 0xffff0000, v165
	v_pk_add_f32 v[108:109], v[108:109], v[152:153]
	v_cvt_pk_bf16_f32 v162, v110, v111
	v_cvt_pk_bf16_f32 v163, v112, v113
	v_cvt_pk_bf16_f32 v164, v106, v107
	v_cvt_pk_bf16_f32 v165, v108, v109
	global_store_dwordx4 v151, v[162:165], s[0:1]
	v_pk_mul_f32 v[110:111], v[110:111], v[110:111]
	v_pk_mul_f32 v[112:113], v[112:113], v[112:113]
	v_pk_mul_f32 v[106:107], v[106:107], v[106:107]
	v_pk_mul_f32 v[108:109], v[108:109], v[108:109]
	v_add_f32_e32 v110, v110, v111
	v_add_f32_e32 v112, v112, v113
	v_add_f32_e32 v106, v106, v107
	v_add_f32_e32 v108, v108, v109
	v_add_f32_e32 v110, v110, v112
	v_add_f32_e32 v106, v106, v108
	v_add_f32_e32 v110, v110, v106
	v_lshlrev_b32_e32 v152, 16, v166
	v_and_b32_e32 v153, 0xffff0000, v166
	v_pk_add_f32 v[102:103], v[102:103], v[152:153]
	v_lshlrev_b32_e32 v152, 16, v167
	v_and_b32_e32 v153, 0xffff0000, v167
	v_pk_add_f32 v[104:105], v[104:105], v[152:153]
	v_lshlrev_b32_e32 v152, 16, v168
	v_and_b32_e32 v153, 0xffff0000, v168
	v_pk_add_f32 v[98:99], v[98:99], v[152:153]
	v_lshlrev_b32_e32 v152, 16, v169
	v_and_b32_e32 v153, 0xffff0000, v169
	v_pk_add_f32 v[100:101], v[100:101], v[152:153]
	v_cvt_pk_bf16_f32 v166, v102, v103
	v_cvt_pk_bf16_f32 v167, v104, v105
	v_cvt_pk_bf16_f32 v168, v98, v99
	v_cvt_pk_bf16_f32 v169, v100, v101
	global_store_dwordx4 v151, v[166:169], s[0:1] offset:256
	v_pk_mul_f32 v[102:103], v[102:103], v[102:103]
	v_pk_mul_f32 v[104:105], v[104:105], v[104:105]
	v_pk_mul_f32 v[98:99], v[98:99], v[98:99]
	v_pk_mul_f32 v[100:101], v[100:101], v[100:101]
	v_add_f32_e32 v102, v102, v103
	v_add_f32_e32 v104, v104, v105
	v_add_f32_e32 v98, v98, v99
	v_add_f32_e32 v100, v100, v101
	v_add_f32_e32 v102, v102, v104
	v_add_f32_e32 v98, v98, v100
	v_add_f32_e32 v102, v102, v98
	v_add_f32_e32 v110, v110, v102
	s_waitcnt vmcnt(14)
; __device__ __forceinline__ unsigned cvt_pk_bf16(float lo, float hi) { const f32x2c_t v = {lo, hi}; return __builtin_bit_cast(unsigned, __builtin_convertvector(v, bf16x2c_t)); }
;     __device__ __forceinline__ void operator()(const f32x4 (&acc)[2][2][4][2], const Unit& u, int wr, int wc, int fr, int fq) const {
;     ...
;             for (int bj = 0; bj < 2; ++bj) {
;                 f32x4 v0 = acc[ai][bj][m][0], v1 = acc[ai][bj][m][1];
;                 v0[0] += __uint_as_float(b[bj].x << 16); v0[1] += __uint_as_float(b[bj].x & 0xffff0000u); v0[2] += __uint_as_float(b[bj].y << 16); v0[3] += __uint_as_float(b[bj].y & 0xffff0000u);
;                 v1[0] += __uint_as_float(b[bj].z << 16); v1[1] += __uint_as_float(b[bj].z & 0xffff0000u); v1[2] += __uint_as_float(b[bj].w << 16); v1[3] += __uint_as_float(b[bj].w & 0xffff0000u);
;                 ss += ((v0[0] * v0[0] + v0[1] * v0[1]) + (v0[2] * v0[2] + v0[3] * v0[3])) + ((v1[0] * v1[0] + v1[1] * v1[1]) + (v1[2] * v1[2] + v1[3] * v1[3]));
;                 u32x4 w; w.x = cvt_pk_bf16(v0[0], v0[1]); w.y = cvt_pk_bf16(v0[2], v0[3]); w.z = cvt_pk_bf16(v1[0], v1[1]); w.w = cvt_pk_bf16(v1[2], v1[3]);
;                 *(u32x4*)(rowp + bj * HALF) = w; }
	s_add_u32 s0, s56, 0x40000
	s_addc_u32 s1, s57, 0
	v_lshlrev_b32_e32 v152, 16, v170
	v_and_b32_e32 v153, 0xffff0000, v170
	v_pk_add_f32 v[94:95], v[94:95], v[152:153]
	v_lshlrev_b32_e32 v152, 16, v171
	v_and_b32_e32 v153, 0xffff0000, v171
	v_pk_add_f32 v[96:97], v[96:97], v[152:153]
	v_lshlrev_b32_e32 v152, 16, v172
	v_and_b32_e32 v153, 0xffff0000, v172
	v_pk_add_f32 v[90:91], v[90:91], v[152:153]
	v_lshlrev_b32_e32 v152, 16, v173
	v_and_b32_e32 v153, 0xffff0000, v173
	v_pk_add_f32 v[92:93], v[92:93], v[152:153]
	v_cvt_pk_bf16_f32 v170, v94, v95
	v_cvt_pk_bf16_f32 v171, v96, v97
	v_cvt_pk_bf16_f32 v172, v90, v91
	v_cvt_pk_bf16_f32 v173, v92, v93
	global_store_dwordx4 v151, v[170:173], s[0:1]
	v_pk_mul_f32 v[94:95], v[94:95], v[94:95]
	v_pk_mul_f32 v[96:97], v[96:97], v[96:97]
	v_pk_mul_f32 v[90:91], v[90:91], v[90:91]
	v_pk_mul_f32 v[92:93], v[92:93], v[92:93]
	v_add_f32_e32 v94, v94, v95
	v_add_f32_e32 v96, v96, v97
	v_add_f32_e32 v90, v90, v91
	v_add_f32_e32 v92, v92, v93
	v_add_f32_e32 v94, v94, v96
	v_add_f32_e32 v90, v90, v92
	v_add_f32_e32 v94, v94, v90
	v_lshlrev_b32_e32 v152, 16, v174
	v_and_b32_e32 v153, 0xffff0000, v174
	v_pk_add_f32 v[86:87], v[86:87], v[152:153]
	v_lshlrev_b32_e32 v152, 16, v175
	v_and_b32_e32 v153, 0xffff0000, v175
	v_pk_add_f32 v[88:89], v[88:89], v[152:153]
	v_lshlrev_b32_e32 v152, 16, v176
	v_and_b32_e32 v153, 0xffff0000, v176
	v_pk_add_f32 v[82:83], v[82:83], v[152:153]
	v_lshlrev_b32_e32 v152, 16, v177
	v_and_b32_e32 v153, 0xffff0000, v177
	v_pk_add_f32 v[84:85], v[84:85], v[152:153]
	v_cvt_pk_bf16_f32 v174, v86, v87
	v_cvt_pk_bf16_f32 v175, v88, v89
	v_cvt_pk_bf16_f32 v176, v82, v83
	v_cvt_pk_bf16_f32 v177, v84, v85
	global_store_dwordx4 v151, v[174:177], s[0:1] offset:256
	v_pk_mul_f32 v[86:87], v[86:87], v[86:87]
	v_pk_mul_f32 v[88:89], v[88:89], v[88:89]
	v_pk_mul_f32 v[82:83], v[82:83], v[82:83]
	v_pk_mul_f32 v[84:85], v[84:85], v[84:85]
	v_add_f32_e32 v86, v86, v87
	v_add_f32_e32 v88, v88, v89
	v_add_f32_e32 v82, v82, v83
	v_add_f32_e32 v84, v84, v85
	v_add_f32_e32 v86, v86, v88
	v_add_f32_e32 v82, v82, v84
	v_add_f32_e32 v86, v86, v82
	v_add_f32_e32 v94, v94, v86
	s_waitcnt vmcnt(14)
	s_add_u32 s0, s56, 0x60000
	s_addc_u32 s1, s57, 0
	v_lshlrev_b32_e32 v152, 16, v178
	v_and_b32_e32 v153, 0xffff0000, v178
	v_pk_add_f32 v[78:79], v[78:79], v[152:153]
	v_lshlrev_b32_e32 v152, 16, v179
	v_and_b32_e32 v153, 0xffff0000, v179
	v_pk_add_f32 v[80:81], v[80:81], v[152:153]
	v_lshlrev_b32_e32 v152, 16, v180
	v_and_b32_e32 v153, 0xffff0000, v180
	v_pk_add_f32 v[74:75], v[74:75], v[152:153]
	v_lshlrev_b32_e32 v152, 16, v181
	v_and_b32_e32 v153, 0xffff0000, v181
	v_pk_add_f32 v[76:77], v[76:77], v[152:153]
	v_cvt_pk_bf16_f32 v178, v78, v79
	v_cvt_pk_bf16_f32 v179, v80, v81
	v_cvt_pk_bf16_f32 v180, v74, v75
	v_cvt_pk_bf16_f32 v181, v76, v77
	global_store_dwordx4 v151, v[178:181], s[0:1]
	v_pk_mul_f32 v[78:79], v[78:79], v[78:79]
	v_pk_mul_f32 v[80:81], v[80:81], v[80:81]
	v_pk_mul_f32 v[74:75], v[74:75], v[74:75]
	v_pk_mul_f32 v[76:77], v[76:77], v[76:77]
	v_add_f32_e32 v78, v78, v79
	v_add_f32_e32 v80, v80, v81
	v_add_f32_e32 v74, v74, v75
	v_add_f32_e32 v76, v76, v77
	v_add_f32_e32 v78, v78, v80
	v_add_f32_e32 v74, v74, v76
	v_add_f32_e32 v78, v78, v74
	v_lshlrev_b32_e32 v152, 16, v182
	v_and_b32_e32 v153, 0xffff0000, v182
	v_pk_add_f32 v[70:71], v[70:71], v[152:153]
	v_lshlrev_b32_e32 v152, 16, v183
	v_and_b32_e32 v153, 0xffff0000, v183
	v_pk_add_f32 v[72:73], v[72:73], v[152:153]
	v_lshlrev_b32_e32 v152, 16, v184
	v_and_b32_e32 v153, 0xffff0000, v184
	v_pk_add_f32 v[66:67], v[66:67], v[152:153]
	v_lshlrev_b32_e32 v152, 16, v185
	v_and_b32_e32 v153, 0xffff0000, v185
	v_pk_add_f32 v[68:69], v[68:69], v[152:153]
	v_cvt_pk_bf16_f32 v182, v70, v71
	v_cvt_pk_bf16_f32 v183, v72, v73
	v_cvt_pk_bf16_f32 v184, v66, v67
	v_cvt_pk_bf16_f32 v185, v68, v69
	global_store_dwordx4 v151, v[182:185], s[0:1] offset:256
	v_pk_mul_f32 v[70:71], v[70:71], v[70:71]
	v_pk_mul_f32 v[72:73], v[72:73], v[72:73]
	v_pk_mul_f32 v[66:67], v[66:67], v[66:67]
	v_pk_mul_f32 v[68:69], v[68:69], v[68:69]
	v_add_f32_e32 v70, v70, v71
	v_add_f32_e32 v72, v72, v73
	v_add_f32_e32 v66, v66, v67
	v_add_f32_e32 v68, v68, v69
	v_add_f32_e32 v70, v70, v72
	v_add_f32_e32 v66, v66, v68
	v_add_f32_e32 v70, v70, v66
	v_add_f32_e32 v78, v78, v70
	s_waitcnt vmcnt(14)
	s_add_u32 s0, s56, 0x100000
	s_addc_u32 s1, s57, 0
	v_lshlrev_b32_e32 v152, 16, v186
	v_and_b32_e32 v153, 0xffff0000, v186
	v_pk_add_f32 v[62:63], v[62:63], v[152:153]
	v_lshlrev_b32_e32 v152, 16, v187
	v_and_b32_e32 v153, 0xffff0000, v187
	v_pk_add_f32 v[64:65], v[64:65], v[152:153]
	v_lshlrev_b32_e32 v152, 16, v188
	v_and_b32_e32 v153, 0xffff0000, v188
	v_pk_add_f32 v[58:59], v[58:59], v[152:153]
	v_lshlrev_b32_e32 v152, 16, v189
	v_and_b32_e32 v153, 0xffff0000, v189
	v_pk_add_f32 v[60:61], v[60:61], v[152:153]
	v_cvt_pk_bf16_f32 v186, v62, v63
	v_cvt_pk_bf16_f32 v187, v64, v65
	v_cvt_pk_bf16_f32 v188, v58, v59
	v_cvt_pk_bf16_f32 v189, v60, v61
	global_store_dwordx4 v151, v[186:189], s[0:1]
	v_pk_mul_f32 v[62:63], v[62:63], v[62:63]
	v_pk_mul_f32 v[64:65], v[64:65], v[64:65]
	v_pk_mul_f32 v[58:59], v[58:59], v[58:59]
	v_pk_mul_f32 v[60:61], v[60:61], v[60:61]
	v_add_f32_e32 v62, v62, v63
	v_add_f32_e32 v64, v64, v65
	v_add_f32_e32 v58, v58, v59
	v_add_f32_e32 v60, v60, v61
	v_add_f32_e32 v62, v62, v64
	v_add_f32_e32 v58, v58, v60
	v_add_f32_e32 v62, v62, v58
	v_lshlrev_b32_e32 v152, 16, v190
	v_and_b32_e32 v153, 0xffff0000, v190
	v_pk_add_f32 v[54:55], v[54:55], v[152:153]
	v_lshlrev_b32_e32 v152, 16, v191
	v_and_b32_e32 v153, 0xffff0000, v191
	v_pk_add_f32 v[56:57], v[56:57], v[152:153]
	v_lshlrev_b32_e32 v152, 16, v192
	v_and_b32_e32 v153, 0xffff0000, v192
	v_pk_add_f32 v[50:51], v[50:51], v[152:153]
	v_lshlrev_b32_e32 v152, 16, v193
	v_and_b32_e32 v153, 0xffff0000, v193
	v_pk_add_f32 v[52:53], v[52:53], v[152:153]
	v_cvt_pk_bf16_f32 v190, v54, v55
	v_cvt_pk_bf16_f32 v191, v56, v57
	v_cvt_pk_bf16_f32 v192, v50, v51
	v_cvt_pk_bf16_f32 v193, v52, v53
	global_store_dwordx4 v151, v[190:193], s[0:1] offset:256
	v_pk_mul_f32 v[54:55], v[54:55], v[54:55]
	v_pk_mul_f32 v[56:57], v[56:57], v[56:57]
	v_pk_mul_f32 v[50:51], v[50:51], v[50:51]
	v_pk_mul_f32 v[52:53], v[52:53], v[52:53]
	v_add_f32_e32 v54, v54, v55
	v_add_f32_e32 v56, v56, v57
	v_add_f32_e32 v50, v50, v51
	v_add_f32_e32 v52, v52, v53
	v_add_f32_e32 v54, v54, v56
	v_add_f32_e32 v50, v50, v52
	v_add_f32_e32 v54, v54, v50
	v_add_f32_e32 v62, v62, v54
	s_waitcnt vmcnt(14)
; __device__ __forceinline__ unsigned cvt_pk_bf16(float lo, float hi) { const f32x2c_t v = {lo, hi}; return __builtin_bit_cast(unsigned, __builtin_convertvector(v, bf16x2c_t)); }
;     __device__ __forceinline__ void operator()(const f32x4 (&acc)[2][2][4][2], const Unit& u, int wr, int wc, int fr, int fq) const {
;     ...
;             for (int bj = 0; bj < 2; ++bj) {
;                 f32x4 v0 = acc[ai][bj][m][0], v1 = acc[ai][bj][m][1];
;                 v0[0] += __uint_as_float(b[bj].x << 16); v0[1] += __uint_as_float(b[bj].x & 0xffff0000u); v0[2] += __uint_as_float(b[bj].y << 16); v0[3] += __uint_as_float(b[bj].y & 0xffff0000u);
;                 v1[0] += __uint_as_float(b[bj].z << 16); v1[1] += __uint_as_float(b[bj].z & 0xffff0000u); v1[2] += __uint_as_float(b[bj].w << 16); v1[3] += __uint_as_float(b[bj].w & 0xffff0000u);
;                 ss += ((v0[0] * v0[0] + v0[1] * v0[1]) + (v0[2] * v0[2] + v0[3] * v0[3])) + ((v1[0] * v1[0] + v1[1] * v1[1]) + (v1[2] * v1[2] + v1[3] * v1[3]));
;                 u32x4 w; w.x = cvt_pk_bf16(v0[0], v0[1]); w.y = cvt_pk_bf16(v0[2], v0[3]); w.z = cvt_pk_bf16(v1[0], v1[1]); w.w = cvt_pk_bf16(v1[2], v1[3]);
;                 *(u32x4*)(rowp + bj * HALF) = w; }
	s_add_u32 s0, s56, 0x120000
	s_addc_u32 s1, s57, 0
	v_lshlrev_b32_e32 v152, 16, v194
	v_and_b32_e32 v153, 0xffff0000, v194
	v_pk_add_f32 v[46:47], v[46:47], v[152:153]
	v_lshlrev_b32_e32 v152, 16, v195
	v_and_b32_e32 v153, 0xffff0000, v195
	v_pk_add_f32 v[48:49], v[48:49], v[152:153]
	v_lshlrev_b32_e32 v152, 16, v196
	v_and_b32_e32 v153, 0xffff0000, v196
	v_pk_add_f32 v[42:43], v[42:43], v[152:153]
	v_lshlrev_b32_e32 v152, 16, v197
	v_and_b32_e32 v153, 0xffff0000, v197
	v_pk_add_f32 v[44:45], v[44:45], v[152:153]
	v_cvt_pk_bf16_f32 v194, v46, v47
	v_cvt_pk_bf16_f32 v195, v48, v49
	v_cvt_pk_bf16_f32 v196, v42, v43
	v_cvt_pk_bf16_f32 v197, v44, v45
	global_store_dwordx4 v151, v[194:197], s[0:1]
	v_pk_mul_f32 v[46:47], v[46:47], v[46:47]
	v_pk_mul_f32 v[48:49], v[48:49], v[48:49]
	v_pk_mul_f32 v[42:43], v[42:43], v[42:43]
	v_pk_mul_f32 v[44:45], v[44:45], v[44:45]
	v_add_f32_e32 v46, v46, v47
	v_add_f32_e32 v48, v48, v49
	v_add_f32_e32 v42, v42, v43
	v_add_f32_e32 v44, v44, v45
	v_add_f32_e32 v46, v46, v48
	v_add_f32_e32 v42, v42, v44
	v_add_f32_e32 v46, v46, v42
	v_lshlrev_b32_e32 v152, 16, v198
	v_and_b32_e32 v153, 0xffff0000, v198
	v_pk_add_f32 v[38:39], v[38:39], v[152:153]
	v_lshlrev_b32_e32 v152, 16, v199
	v_and_b32_e32 v153, 0xffff0000, v199
	v_pk_add_f32 v[40:41], v[40:41], v[152:153]
	v_lshlrev_b32_e32 v152, 16, v200
	v_and_b32_e32 v153, 0xffff0000, v200
	v_pk_add_f32 v[34:35], v[34:35], v[152:153]
	v_lshlrev_b32_e32 v152, 16, v201
	v_and_b32_e32 v153, 0xffff0000, v201
	v_pk_add_f32 v[36:37], v[36:37], v[152:153]
	v_cvt_pk_bf16_f32 v198, v38, v39
	v_cvt_pk_bf16_f32 v199, v40, v41
	v_cvt_pk_bf16_f32 v200, v34, v35
	v_cvt_pk_bf16_f32 v201, v36, v37
	global_store_dwordx4 v151, v[198:201], s[0:1] offset:256
	v_pk_mul_f32 v[38:39], v[38:39], v[38:39]
	v_pk_mul_f32 v[40:41], v[40:41], v[40:41]
	v_pk_mul_f32 v[34:35], v[34:35], v[34:35]
	v_pk_mul_f32 v[36:37], v[36:37], v[36:37]
	v_add_f32_e32 v38, v38, v39
	v_add_f32_e32 v40, v40, v41
	v_add_f32_e32 v34, v34, v35
	v_add_f32_e32 v36, v36, v37
	v_add_f32_e32 v38, v38, v40
	v_add_f32_e32 v34, v34, v36
	v_add_f32_e32 v38, v38, v34
	v_add_f32_e32 v46, v46, v38
	s_waitcnt vmcnt(14)
	s_add_u32 s0, s56, 0x140000
	s_addc_u32 s1, s57, 0
	v_lshlrev_b32_e32 v152, 16, v202
	v_and_b32_e32 v153, 0xffff0000, v202
	v_pk_add_f32 v[30:31], v[30:31], v[152:153]
	v_lshlrev_b32_e32 v152, 16, v203
	v_and_b32_e32 v153, 0xffff0000, v203
	v_pk_add_f32 v[32:33], v[32:33], v[152:153]
	v_lshlrev_b32_e32 v152, 16, v204
	v_and_b32_e32 v153, 0xffff0000, v204
	v_pk_add_f32 v[26:27], v[26:27], v[152:153]
	v_lshlrev_b32_e32 v152, 16, v205
	v_and_b32_e32 v153, 0xffff0000, v205
	v_pk_add_f32 v[28:29], v[28:29], v[152:153]
	v_cvt_pk_bf16_f32 v202, v30, v31
	v_cvt_pk_bf16_f32 v203, v32, v33
	v_cvt_pk_bf16_f32 v204, v26, v27
	v_cvt_pk_bf16_f32 v205, v28, v29
	global_store_dwordx4 v151, v[202:205], s[0:1]
	v_pk_mul_f32 v[30:31], v[30:31], v[30:31]
	v_pk_mul_f32 v[32:33], v[32:33], v[32:33]
	v_pk_mul_f32 v[26:27], v[26:27], v[26:27]
	v_pk_mul_f32 v[28:29], v[28:29], v[28:29]
	v_add_f32_e32 v30, v30, v31
	v_add_f32_e32 v32, v32, v33
	v_add_f32_e32 v26, v26, v27
	v_add_f32_e32 v28, v28, v29
	v_add_f32_e32 v30, v30, v32
	v_add_f32_e32 v26, v26, v28
	v_add_f32_e32 v30, v30, v26
	v_lshlrev_b32_e32 v152, 16, v206
	v_and_b32_e32 v153, 0xffff0000, v206
	v_pk_add_f32 v[22:23], v[22:23], v[152:153]
	v_lshlrev_b32_e32 v152, 16, v207
	v_and_b32_e32 v153, 0xffff0000, v207
	v_pk_add_f32 v[24:25], v[24:25], v[152:153]
	v_lshlrev_b32_e32 v152, 16, v208
	v_and_b32_e32 v153, 0xffff0000, v208
	v_pk_add_f32 v[18:19], v[18:19], v[152:153]
	v_lshlrev_b32_e32 v152, 16, v209
	v_and_b32_e32 v153, 0xffff0000, v209
	v_pk_add_f32 v[20:21], v[20:21], v[152:153]
	v_cvt_pk_bf16_f32 v206, v22, v23
	v_cvt_pk_bf16_f32 v207, v24, v25
	v_cvt_pk_bf16_f32 v208, v18, v19
	v_cvt_pk_bf16_f32 v209, v20, v21
	global_store_dwordx4 v151, v[206:209], s[0:1] offset:256
	v_pk_mul_f32 v[22:23], v[22:23], v[22:23]
	v_pk_mul_f32 v[24:25], v[24:25], v[24:25]
	v_pk_mul_f32 v[18:19], v[18:19], v[18:19]
	v_pk_mul_f32 v[20:21], v[20:21], v[20:21]
	v_add_f32_e32 v22, v22, v23
	v_add_f32_e32 v24, v24, v25
	v_add_f32_e32 v18, v18, v19
	v_add_f32_e32 v20, v20, v21
	v_add_f32_e32 v22, v22, v24
	v_add_f32_e32 v18, v18, v20
	v_add_f32_e32 v22, v22, v18
	v_add_f32_e32 v30, v30, v22
	s_waitcnt vmcnt(12)
; __device__ __forceinline__ unsigned cvt_pk_bf16(float lo, float hi) { const f32x2c_t v = {lo, hi}; return __builtin_bit_cast(unsigned, __builtin_convertvector(v, bf16x2c_t)); }
;     __device__ __forceinline__ void operator()(const f32x4 (&acc)[2][2][4][2], const Unit& u, int wr, int wc, int fr, int fq) const {
;     ...
;             for (int bj = 0; bj < 2; ++bj) {
;                 f32x4 v0 = acc[ai][bj][m][0], v1 = acc[ai][bj][m][1];
;                 v0[0] += __uint_as_float(b[bj].x << 16); v0[1] += __uint_as_float(b[bj].x & 0xffff0000u); v0[2] += __uint_as_float(b[bj].y << 16); v0[3] += __uint_as_float(b[bj].y & 0xffff0000u);
;                 v1[0] += __uint_as_float(b[bj].z << 16); v1[1] += __uint_as_float(b[bj].z & 0xffff0000u); v1[2] += __uint_as_float(b[bj].w << 16); v1[3] += __uint_as_float(b[bj].w & 0xffff0000u);
;                 ss += ((v0[0] * v0[0] + v0[1] * v0[1]) + (v0[2] * v0[2] + v0[3] * v0[3])) + ((v1[0] * v1[0] + v1[1] * v1[1]) + (v1[2] * v1[2] + v1[3] * v1[3]));
;                 u32x4 w; w.x = cvt_pk_bf16(v0[0], v0[1]); w.y = cvt_pk_bf16(v0[2], v0[3]); w.z = cvt_pk_bf16(v1[0], v1[1]); w.w = cvt_pk_bf16(v1[2], v1[3]);
;                 *(u32x4*)(rowp + bj * HALF) = w; }
;             ss += __shfl_xor(ss, 16); ss += __shfl_xor(ss, 32);
;             if (fq == 0) part[(size_t)row * 64 + u.pn * 4 + wc] = ss; }
	s_add_u32 s0, s56, 0x160000
	s_addc_u32 s1, s57, 0
	v_lshlrev_b32_e32 v152, 16, v118
	v_and_b32_e32 v153, 0xffff0000, v118
	v_pk_add_f32 v[12:13], v[12:13], v[152:153]
	v_lshlrev_b32_e32 v152, 16, v119
	v_and_b32_e32 v153, 0xffff0000, v119
	v_pk_add_f32 v[14:15], v[14:15], v[152:153]
	v_lshlrev_b32_e32 v152, 16, v120
	v_and_b32_e32 v153, 0xffff0000, v120
	v_pk_add_f32 v[8:9], v[8:9], v[152:153]
	v_lshlrev_b32_e32 v152, 16, v121
	v_and_b32_e32 v153, 0xffff0000, v121
	v_pk_add_f32 v[10:11], v[10:11], v[152:153]
	v_cvt_pk_bf16_f32 v118, v12, v13
	v_cvt_pk_bf16_f32 v119, v14, v15
	v_cvt_pk_bf16_f32 v120, v8, v9
	v_cvt_pk_bf16_f32 v121, v10, v11
	global_store_dwordx4 v151, v[118:121], s[0:1]
	v_pk_mul_f32 v[12:13], v[12:13], v[12:13]
	v_pk_mul_f32 v[14:15], v[14:15], v[14:15]
	v_pk_mul_f32 v[8:9], v[8:9], v[8:9]
	v_pk_mul_f32 v[10:11], v[10:11], v[10:11]
	v_add_f32_e32 v12, v12, v13
	v_add_f32_e32 v14, v14, v15
	v_add_f32_e32 v8, v8, v9
	v_add_f32_e32 v10, v10, v11
	v_add_f32_e32 v12, v12, v14
	v_add_f32_e32 v8, v8, v10
	v_add_f32_e32 v12, v12, v8
	v_lshlrev_b32_e32 v152, 16, v122
	v_and_b32_e32 v153, 0xffff0000, v122
	v_pk_add_f32 v[4:5], v[4:5], v[152:153]
	v_lshlrev_b32_e32 v152, 16, v123
	v_and_b32_e32 v153, 0xffff0000, v123
	v_pk_add_f32 v[6:7], v[6:7], v[152:153]
	v_lshlrev_b32_e32 v152, 16, v124
	v_and_b32_e32 v153, 0xffff0000, v124
	v_pk_add_f32 v[0:1], v[0:1], v[152:153]
	v_lshlrev_b32_e32 v152, 16, v125
	v_and_b32_e32 v153, 0xffff0000, v125
	v_pk_add_f32 v[2:3], v[2:3], v[152:153]
	v_cvt_pk_bf16_f32 v122, v4, v5
	v_cvt_pk_bf16_f32 v123, v6, v7
	v_cvt_pk_bf16_f32 v124, v0, v1
	v_cvt_pk_bf16_f32 v125, v2, v3
	global_store_dwordx4 v151, v[122:125], s[0:1] offset:256
	v_pk_mul_f32 v[4:5], v[4:5], v[4:5]
	v_pk_mul_f32 v[6:7], v[6:7], v[6:7]
	v_pk_mul_f32 v[0:1], v[0:1], v[0:1]
	v_pk_mul_f32 v[2:3], v[2:3], v[2:3]
	v_add_f32_e32 v4, v4, v5
	v_add_f32_e32 v6, v6, v7
	v_add_f32_e32 v0, v0, v1
	v_add_f32_e32 v2, v2, v3
	v_add_f32_e32 v4, v4, v6
	v_add_f32_e32 v0, v0, v2
	v_add_f32_e32 v4, v4, v0
	v_add_f32_e32 v12, v12, v4
	ds_bpermute_b32 v127, v159, v126
	ds_bpermute_b32 v111, v159, v110
	ds_bpermute_b32 v95, v159, v94
	ds_bpermute_b32 v79, v159, v78
	ds_bpermute_b32 v63, v159, v62
	ds_bpermute_b32 v47, v159, v46
	ds_bpermute_b32 v31, v159, v30
	ds_bpermute_b32 v13, v159, v12
	s_waitcnt lgkmcnt(7)
	v_add_f32_e32 v126, v126, v127
	ds_bpermute_b32 v127, v160, v126
	s_waitcnt lgkmcnt(7)
	v_add_f32_e32 v110, v110, v111
	ds_bpermute_b32 v111, v160, v110
	s_waitcnt lgkmcnt(7)
	v_add_f32_e32 v94, v94, v95
	ds_bpermute_b32 v95, v160, v94
	s_waitcnt lgkmcnt(7)
	v_add_f32_e32 v78, v78, v79
	ds_bpermute_b32 v79, v160, v78
	s_waitcnt lgkmcnt(7)
	v_add_f32_e32 v62, v62, v63
	ds_bpermute_b32 v63, v160, v62
	s_waitcnt lgkmcnt(7)
	v_add_f32_e32 v46, v46, v47
	ds_bpermute_b32 v47, v160, v46
	s_waitcnt lgkmcnt(7)
	v_add_f32_e32 v30, v30, v31
	ds_bpermute_b32 v31, v160, v30
	s_waitcnt lgkmcnt(7)
	v_add_f32_e32 v12, v12, v13
	ds_bpermute_b32 v13, v160, v12
	s_and_saveexec_b64 s[16:17], s[4:5]
	s_cbranch_execz .Lepires_skip_g4
	s_waitcnt lgkmcnt(7)
	v_add_f32_e32 v126, v126, v127
	global_store_dword v149, v126, s[76:77]
	s_waitcnt lgkmcnt(6)
	v_add_f32_e32 v110, v110, v111
	s_add_u32 s0, s76, 0x1000
	s_addc_u32 s1, s77, 0
	global_store_dword v149, v110, s[0:1]
	s_waitcnt lgkmcnt(5)
	v_add_f32_e32 v94, v94, v95
	s_add_u32 s0, s76, 0x2000
	s_addc_u32 s1, s77, 0
	global_store_dword v149, v94, s[0:1]
	s_waitcnt lgkmcnt(4)
	v_add_f32_e32 v78, v78, v79
	s_add_u32 s0, s76, 0x3000
	s_addc_u32 s1, s77, 0
	global_store_dword v149, v78, s[0:1]
	s_waitcnt lgkmcnt(3)
	v_add_f32_e32 v62, v62, v63
	s_add_u32 s0, s76, 0x8000
	s_addc_u32 s1, s77, 0
	global_store_dword v149, v62, s[0:1]
	s_waitcnt lgkmcnt(2)
	v_add_f32_e32 v46, v46, v47
	s_add_u32 s0, s76, 0x9000
	s_addc_u32 s1, s77, 0
	global_store_dword v149, v46, s[0:1]
	s_waitcnt lgkmcnt(1)
	v_add_f32_e32 v30, v30, v31
	s_add_u32 s0, s76, 0xa000
	s_addc_u32 s1, s77, 0
	global_store_dword v149, v30, s[0:1]
	s_waitcnt lgkmcnt(0)
	v_add_f32_e32 v12, v12, v13
	s_add_u32 s0, s76, 0xb000
	s_addc_u32 s1, s77, 0
	global_store_dword v149, v12, s[0:1]
.Lepires_skip_g4:
	s_or_b64 exec, exec, s[16:17]
	s_waitcnt lgkmcnt(0)
	s_andn2_b64 vcc, exec, s[20:21]
	s_mov_b64 s[0:1], -1
	s_movk_i32 s73, 0x1000
	s_mov_b32 s78, 0xf800000
	s_cbranch_vccnz .LBB0_844
	s_andn2_b64 vcc, exec, s[6:7]
	s_cbranch_vccnz .LBB0_843
	s_barrier
	s_branch .LBB0_843
